# conversion LDS swizzle + shift 4608 conversion items from GU(0) tail to P_in(1) tail (CJ_C0 62536->57928)
# speedup vs baseline: 1.0085x; 1.0085x over previous
.LBB0_313:
	s_or_b64 exec, exec, s[2:3]
	v_readlane_b32 s8, v255, 45
	v_readlane_b32 s9, v255, 46
	s_and_b64 s[2:3], s[8:9], exec
	s_mov_b32 s2, 0x12b00
	s_cselect_b32 s61, 0x8000, s2
	s_ashr_i32 s20, s10, 6
	v_and_b32_e32 v130, 63, v0
	s_mul_i32 s2, s20, 0x2500
	s_add_i32 s6, s2, 0
	v_bfe_u32 v133, v0, 4, 2
	v_lshlrev_b32_e32 v2, 2, v130
	s_and_b64 s[2:3], s[8:9], exec
	v_and_b32_e32 v132, 60, v2
	v_or_b32_e32 v135, 4, v133
	v_or_b32_e32 v138, 8, v133
	v_or_b32_e32 v139, 12, v133
	v_or_b32_e32 v140, 16, v133
	v_or_b32_e32 v141, 20, v133
	v_or_b32_e32 v142, 24, v133
	v_or_b32_e32 v143, 28, v133
	v_or_b32_e32 v144, 32, v133
	v_or_b32_e32 v145, 36, v133
	v_or_b32_e32 v146, 40, v133
	v_or_b32_e32 v147, 44, v133
	v_or_b32_e32 v148, 48, v133
	v_or_b32_e32 v149, 52, v133
	v_or_b32_e32 v150, 56, v133
	v_or_b32_e32 v151, 60, v133
	v_add_u32_e32 v152, s6, v2
	v_mov_b32_e32 v2, s6
	v_bfe_u32 v154, v0, 3, 3
	v_and_b32_e32 v0, 7, v0
	s_movk_i32 s2, 0x2628
	v_mad_u32_u24 v2, v132, s52, v2
	v_lshlrev_b32_e32 v3, 1, v133
	v_lshlrev_b32_e32 v4, 1, v135
	v_lshlrev_b32_e32 v5, 1, v138
	v_lshlrev_b32_e32 v6, 1, v139
	v_lshlrev_b32_e32 v7, 1, v140
	v_lshlrev_b32_e32 v8, 1, v141
	v_lshlrev_b32_e32 v9, 1, v142
	v_lshlrev_b32_e32 v10, 1, v143
	v_lshlrev_b32_e32 v11, 1, v144
	v_lshlrev_b32_e32 v12, 1, v145
	v_lshlrev_b32_e32 v13, 1, v146
	v_lshlrev_b32_e32 v14, 1, v147
	v_lshlrev_b32_e32 v15, 1, v148
	v_lshlrev_b32_e32 v16, 1, v149
	v_lshlrev_b32_e32 v17, 1, v150
	v_lshlrev_b32_e32 v18, 1, v151
	v_lshl_add_u32 v19, v0, 4, s6
	v_lshlrev_b32_e32 v134, 3, v0
	v_mul_u32_u24_e32 v0, 0x90, v154
	s_cselect_b32 s21, s2, 0xe248
	v_lshl_add_u32 v153, v133, 2, s6
	v_or_b32_e32 v155, 8, v154
	v_or_b32_e32 v156, 16, v154
	v_or_b32_e32 v157, 24, v154
	v_or_b32_e32 v158, 32, v154
	v_or_b32_e32 v159, 40, v154
	v_or_b32_e32 v160, 48, v154
	v_or_b32_e32 v161, 56, v154
	v_lshlrev_b32_e32 v5, 1, v134
	v_add_u32_e32 v3, v2, v3
	v_add_u32_e32 v4, v2, v4
	v_add_u32_e32 v162, v3, v5
	v_add_u32_e32 v163, v4, v5
	v_xor_b32_e32 v6, 16, v5
	v_add_u32_e32 v164, v3, v6
	v_add_u32_e32 v165, v4, v6
	v_xor_b32_e32 v6, 32, v5
	v_add_u32_e32 v166, v3, v6
	v_add_u32_e32 v167, v4, v6
	v_xor_b32_e32 v6, 48, v5
	v_add_u32_e32 v168, v3, v6
	v_add_u32_e32 v169, v4, v6
	v_xor_b32_e32 v6, 64, v5
	v_add_u32_e32 v180, v3, v6
	v_add_u32_e32 v181, v4, v6
	v_xor_b32_e32 v6, 0x50, v5
	v_add_u32_e32 v182, v3, v6
	v_add_u32_e32 v183, v4, v6
	v_xor_b32_e32 v6, 0x60, v5
	v_add_u32_e32 v184, v3, v6
	v_add_u32_e32 v185, v4, v6
	v_xor_b32_e32 v6, 0x70, v5
	v_add_u32_e32 v186, v3, v6
	v_add_u32_e32 v187, v4, v6
	v_add_u32_e32 v7, v19, v0
	v_sub_u32_e32 v7, v7, v5
	v_lshrrev_b32_e32 v8, 2, v154
	v_lshlrev_b32_e32 v8, 4, v8
	v_xor_b32_e32 v8, v8, v5
	v_add_u32_e32 v188, v7, v8
	v_xor_b32_e32 v9, 32, v8
	v_add_u32_e32 v244, v7, v9
	v_xor_b32_e32 v9, 64, v8
	v_add_u32_e32 v245, v7, v9
	v_xor_b32_e32 v9, 0x60, v8
	v_add_u32_e32 v246, v7, v9
	s_branch .LBB0_316

.LBB0_968:
	s_or_b64 exec, exec, s[2:3]
	v_readlane_b32 s2, v255, 45
	v_readlane_b32 s3, v255, 46
	s_and_b64 s[2:3], s[2:3], exec
	s_mov_b32 s2, 0x15600
	s_cselect_b32 s20, 0xe248, s2
	s_ashr_i32 s21, s18, 6
	v_and_b32_e32 v130, 63, v0
	s_mul_i32 s2, s21, 0x2500
	s_add_i32 s2, s2, 0
	v_bfe_u32 v133, v0, 4, 2
	v_lshlrev_b32_e32 v2, 2, v130
	v_and_b32_e32 v132, 60, v2
	v_or_b32_e32 v135, 4, v133
	v_or_b32_e32 v138, 8, v133
	v_or_b32_e32 v139, 12, v133
	v_or_b32_e32 v140, 16, v133
	v_or_b32_e32 v141, 20, v133
	v_or_b32_e32 v142, 24, v133
	v_or_b32_e32 v143, 28, v133
	v_or_b32_e32 v144, 32, v133
	v_or_b32_e32 v145, 36, v133
	v_or_b32_e32 v146, 40, v133
	v_or_b32_e32 v147, 44, v133
	v_or_b32_e32 v148, 48, v133
	v_or_b32_e32 v149, 52, v133
	v_or_b32_e32 v150, 56, v133
	v_or_b32_e32 v151, 60, v133
	v_add_u32_e32 v152, s2, v2
	v_mov_b32_e32 v2, s2
	s_movk_i32 s3, 0x90
	v_bfe_u32 v154, v0, 3, 3
	v_and_b32_e32 v0, 7, v0
	v_mad_u32_u24 v2, v132, s3, v2
	v_lshlrev_b32_e32 v3, 1, v133
	v_lshlrev_b32_e32 v4, 1, v135
	v_lshlrev_b32_e32 v5, 1, v138
	v_lshlrev_b32_e32 v6, 1, v139
	v_lshlrev_b32_e32 v7, 1, v140
	v_lshlrev_b32_e32 v8, 1, v141
	v_lshlrev_b32_e32 v9, 1, v142
	v_lshlrev_b32_e32 v10, 1, v143
	v_lshlrev_b32_e32 v11, 1, v144
	v_lshlrev_b32_e32 v12, 1, v145
	v_lshlrev_b32_e32 v13, 1, v146
	v_lshlrev_b32_e32 v14, 1, v147
	v_lshlrev_b32_e32 v15, 1, v148
	v_lshlrev_b32_e32 v16, 1, v149
	v_lshlrev_b32_e32 v17, 1, v150
	v_lshlrev_b32_e32 v18, 1, v151
	v_lshl_add_u32 v19, v0, 4, s2
	v_lshlrev_b32_e32 v134, 3, v0
	v_mul_u32_u24_e32 v0, 0x90, v154
	v_lshl_add_u32 v153, v133, 2, s2
	v_or_b32_e32 v155, 8, v154
	v_or_b32_e32 v156, 16, v154
	v_or_b32_e32 v157, 24, v154
	v_or_b32_e32 v158, 32, v154
	v_or_b32_e32 v159, 40, v154
	v_or_b32_e32 v160, 48, v154
	v_or_b32_e32 v161, 56, v154
	v_lshlrev_b32_e32 v5, 1, v134
	v_add_u32_e32 v3, v2, v3
	v_add_u32_e32 v4, v2, v4
	v_add_u32_e32 v162, v3, v5
	v_add_u32_e32 v163, v4, v5
	v_xor_b32_e32 v6, 16, v5
	v_add_u32_e32 v164, v3, v6
	v_add_u32_e32 v165, v4, v6
	v_xor_b32_e32 v6, 32, v5
	v_add_u32_e32 v166, v3, v6
	v_add_u32_e32 v167, v4, v6
	v_xor_b32_e32 v6, 48, v5
	v_add_u32_e32 v168, v3, v6
	v_add_u32_e32 v169, v4, v6
	v_xor_b32_e32 v6, 64, v5
	v_add_u32_e32 v180, v3, v6
	v_add_u32_e32 v181, v4, v6
	v_xor_b32_e32 v6, 0x50, v5
	v_add_u32_e32 v182, v3, v6
	v_add_u32_e32 v183, v4, v6
	v_xor_b32_e32 v6, 0x60, v5
	v_add_u32_e32 v184, v3, v6
	v_add_u32_e32 v185, v4, v6
	v_xor_b32_e32 v6, 0x70, v5
	v_add_u32_e32 v186, v3, v6
	v_add_u32_e32 v187, v4, v6
	v_add_u32_e32 v7, v19, v0
	v_sub_u32_e32 v7, v7, v5
	v_lshrrev_b32_e32 v8, 2, v154
	v_lshlrev_b32_e32 v8, 4, v8
	v_xor_b32_e32 v8, v8, v5
	v_add_u32_e32 v188, v7, v8
	v_xor_b32_e32 v9, 32, v8
	v_add_u32_e32 v244, v7, v9
	v_xor_b32_e32 v9, 64, v8
	v_add_u32_e32 v245, v7, v9
	v_xor_b32_e32 v9, 0x60, v8
	v_add_u32_e32 v246, v7, v9
	s_branch .LBB0_971
